# scan: next-chunk prefetch loads stay in flight across stage 2 (loaded straight into carried registers, wait moved to next chunk top, counted past the 8 output stores); phase0 x->bf16 row loop software
# speedup vs baseline: 1.1935x; 1.0089x over previous
.LBB0_28:
	s_cmp_lt_i32 s62, 1
	s_cselect_b64 s[6:7], -1, 0
	s_cmp_gt_i32 s61, 0
	s_cselect_b64 s[8:9], -1, 0
	s_and_b64 s[6:7], s[6:7], s[8:9]
	s_andn2_b64 vcc, exec, s[6:7]
	s_cbranch_vccnz .LBB0_179
	v_lshrrev_b32_e32 v0, 6, v192
	v_lshl_add_u32 v0, s2, 3, v0
	s_mov_b32 s3, 0x8000
	s_mov_b64 s[6:7], s[0:1]
	s_mov_b64 s[8:9], s[0:1]
	s_mov_b64 s[16:17], s[0:1]
	v_cmp_gt_i32_e32 vcc, s3, v0
	s_and_saveexec_b64 s[12:13], vcc
	s_cbranch_execz .LBB0_34
	s_load_dwordx2 s[24:25], s[8:9], 0x100
	s_load_dwordx2 s[14:15], s[6:7], 0x0
	v_and_b32_e32 v1, 63, v192
	v_readfirstlane_b32 s27, v0
	v_lshlrev_b32_e32 v2, 2, v1
	v_lshlrev_b32_e32 v6, 4, v1
	v_lshlrev_b32_e32 v7, 3, v1
	v_cmp_gt_u32_e64 s[28:29], 16, v1
	v_cmp_eq_u32_e64 s[6:7], 0, v1
	s_lshl_b32 s3, s22, 3
	s_waitcnt lgkmcnt(0)
	s_add_u32 s16, s24, 0x16000000
	s_addc_u32 s17, s25, 0
	s_add_u32 s40, s24, 0x1a000000
	s_addc_u32 s41, s25, 0
	s_lshl_b32 s30, s27, 12
	s_add_u32 s30, s14, s30
	s_addc_u32 s31, s15, 0
	global_load_dwordx4 v[32:35], v6, s[30:31]
	global_load_dwordx4 v[36:39], v6, s[30:31] offset:1024
	global_load_dwordx4 v[40:43], v6, s[30:31] offset:2048
	global_load_dwordx4 v[44:47], v6, s[30:31] offset:3072
	s_add_i32 s35, s27, s3
	s_min_i32 s36, s35, 0x7fff
	s_lshl_b32 s30, s36, 12
	s_add_u32 s30, s14, s30
	s_addc_u32 s31, s15, 0
	global_load_dwordx4 v[48:51], v6, s[30:31]
	global_load_dwordx4 v[52:55], v6, s[30:31] offset:1024
	global_load_dwordx4 v[56:59], v6, s[30:31] offset:2048
	global_load_dwordx4 v[60:63], v6, s[30:31] offset:3072
	s_lshl_b32 s37, s27, 11
	s_add_u32 s38, s16, s37
	s_addc_u32 s39, s17, 0
	s_lshl_b32 s37, s27, 6
	s_add_u32 s42, s40, s37
	s_addc_u32 s43, s41, 0
	s_waitcnt vmcnt(7)
	v_cvt_pk_bf16_f32 v12, v32, v33
	v_cvt_pk_bf16_f32 v13, v34, v35
	global_store_dwordx2 v7, v[12:13], s[38:39]
	v_mul_f32_e32 v3, v33, v33
	v_mul_f32_e32 v8, v35, v35
	v_fmac_f32_e32 v3, v32, v32
	v_fmac_f32_e32 v8, v34, v34
	v_add_f32_e32 v3, v3, v8
	s_waitcnt vmcnt(7)
	v_cvt_pk_bf16_f32 v12, v36, v37
	v_cvt_pk_bf16_f32 v13, v38, v39
	global_store_dwordx2 v7, v[12:13], s[38:39] offset:512
	v_mul_f32_e32 v9, v37, v37
	v_mul_f32_e32 v8, v39, v39
	v_fmac_f32_e32 v9, v36, v36
	v_fmac_f32_e32 v8, v38, v38
	v_add_f32_e32 v9, v9, v8
	v_add_f32_e32 v3, v3, v9
	s_waitcnt vmcnt(7)
	v_cvt_pk_bf16_f32 v12, v40, v41
	v_cvt_pk_bf16_f32 v13, v42, v43
	global_store_dwordx2 v7, v[12:13], s[38:39] offset:1024
	v_mul_f32_e32 v9, v41, v41
	v_mul_f32_e32 v8, v43, v43
	v_fmac_f32_e32 v9, v40, v40
	v_fmac_f32_e32 v8, v42, v42
	v_add_f32_e32 v9, v9, v8
	v_add_f32_e32 v3, v3, v9
	s_waitcnt vmcnt(7)
	v_cvt_pk_bf16_f32 v12, v44, v45
	v_cvt_pk_bf16_f32 v13, v46, v47
	global_store_dwordx2 v7, v[12:13], s[38:39] offset:1536
	v_mul_f32_e32 v9, v45, v45
	v_mul_f32_e32 v8, v47, v47
	v_fmac_f32_e32 v9, v44, v44
	v_fmac_f32_e32 v8, v46, v46
	v_add_f32_e32 v9, v9, v8
	v_add_f32_e32 v3, v3, v9
	s_nop 1
	v_add_f32_dpp v3, v3, v3 quad_perm:[1,0,3,2] row_mask:0xf bank_mask:0xf bound_ctrl:1
	s_nop 1
	v_add_f32_dpp v3, v3, v3 quad_perm:[2,3,0,1] row_mask:0xf bank_mask:0xf bound_ctrl:1
	s_nop 1
	v_add_f32_dpp v3, v3, v3 row_half_mirror row_mask:0xf bank_mask:0xf bound_ctrl:1
	s_nop 1
	v_add_f32_dpp v3, v3, v3 row_mirror row_mask:0xf bank_mask:0xf bound_ctrl:1
	v_mov_b32_e32 v8, v3
	s_nop 1
	v_permlane16_swap_b32_e32 v3, v8
	v_add_f32_e32 v3, v3, v8
	v_mov_b32_e32 v8, v3
	s_nop 1
	v_permlane32_swap_b32_e32 v3, v8
	v_add_f32_e32 v3, v3, v8
	v_cndmask_b32_e64 v3, 0, v3, s[6:7]
	s_and_saveexec_b64 s[8:9], s[28:29]
	global_store_dword v2, v3, s[42:43]
	s_or_b64 exec, exec, s[8:9]
	s_cmp_gt_i32 s35, 0x7fff
	s_cbranch_scc1 .Lp0a_done
	s_mov_b32 s27, s35
.Lp0a_loop:
	s_add_i32 s35, s27, s3
	s_min_i32 s36, s35, 0x7fff
	s_lshl_b32 s30, s36, 12
	s_add_u32 s30, s14, s30
	s_addc_u32 s31, s15, 0
	global_load_dwordx4 v[32:35], v6, s[30:31]
	global_load_dwordx4 v[36:39], v6, s[30:31] offset:1024
	global_load_dwordx4 v[40:43], v6, s[30:31] offset:2048
	global_load_dwordx4 v[44:47], v6, s[30:31] offset:3072
	s_lshl_b32 s37, s27, 11
	s_add_u32 s38, s16, s37
	s_addc_u32 s39, s17, 0
	s_lshl_b32 s37, s27, 6
	s_add_u32 s42, s40, s37
	s_addc_u32 s43, s41, 0
	s_waitcnt vmcnt(12)
	v_cvt_pk_bf16_f32 v12, v48, v49
	v_cvt_pk_bf16_f32 v13, v50, v51
	global_store_dwordx2 v7, v[12:13], s[38:39]
	v_mul_f32_e32 v3, v49, v49
	v_mul_f32_e32 v8, v51, v51
	v_fmac_f32_e32 v3, v48, v48
	v_fmac_f32_e32 v8, v50, v50
	v_add_f32_e32 v3, v3, v8
	s_waitcnt vmcnt(12)
	v_cvt_pk_bf16_f32 v12, v52, v53
	v_cvt_pk_bf16_f32 v13, v54, v55
	global_store_dwordx2 v7, v[12:13], s[38:39] offset:512
	v_mul_f32_e32 v9, v53, v53
	v_mul_f32_e32 v8, v55, v55
	v_fmac_f32_e32 v9, v52, v52
	v_fmac_f32_e32 v8, v54, v54
	v_add_f32_e32 v9, v9, v8
	v_add_f32_e32 v3, v3, v9
	s_waitcnt vmcnt(12)
	v_cvt_pk_bf16_f32 v12, v56, v57
	v_cvt_pk_bf16_f32 v13, v58, v59
	global_store_dwordx2 v7, v[12:13], s[38:39] offset:1024
	v_mul_f32_e32 v9, v57, v57
	v_mul_f32_e32 v8, v59, v59
	v_fmac_f32_e32 v9, v56, v56
	v_fmac_f32_e32 v8, v58, v58
	v_add_f32_e32 v9, v9, v8
	v_add_f32_e32 v3, v3, v9
	s_waitcnt vmcnt(12)
	v_cvt_pk_bf16_f32 v12, v60, v61
	v_cvt_pk_bf16_f32 v13, v62, v63
	global_store_dwordx2 v7, v[12:13], s[38:39] offset:1536
	v_mul_f32_e32 v9, v61, v61
	v_mul_f32_e32 v8, v63, v63
	v_fmac_f32_e32 v9, v60, v60
	v_fmac_f32_e32 v8, v62, v62
	v_add_f32_e32 v9, v9, v8
	v_add_f32_e32 v3, v3, v9
	s_nop 1
	v_add_f32_dpp v3, v3, v3 quad_perm:[1,0,3,2] row_mask:0xf bank_mask:0xf bound_ctrl:1
	s_nop 1
	v_add_f32_dpp v3, v3, v3 quad_perm:[2,3,0,1] row_mask:0xf bank_mask:0xf bound_ctrl:1
	s_nop 1
	v_add_f32_dpp v3, v3, v3 row_half_mirror row_mask:0xf bank_mask:0xf bound_ctrl:1
	s_nop 1
	v_add_f32_dpp v3, v3, v3 row_mirror row_mask:0xf bank_mask:0xf bound_ctrl:1
	v_mov_b32_e32 v8, v3
	s_nop 1
	v_permlane16_swap_b32_e32 v3, v8
	v_add_f32_e32 v3, v3, v8
	v_mov_b32_e32 v8, v3
	s_nop 1
	v_permlane32_swap_b32_e32 v3, v8
	v_add_f32_e32 v3, v3, v8
	v_cndmask_b32_e64 v3, 0, v3, s[6:7]
	s_and_saveexec_b64 s[8:9], s[28:29]
	global_store_dword v2, v3, s[42:43]
	s_or_b64 exec, exec, s[8:9]
	s_cmp_gt_i32 s35, 0x7fff
	s_cbranch_scc1 .Lp0a_done
	s_mov_b32 s27, s35
	s_add_i32 s35, s27, s3
	s_min_i32 s36, s35, 0x7fff
	s_lshl_b32 s30, s36, 12
	s_add_u32 s30, s14, s30
	s_addc_u32 s31, s15, 0
	global_load_dwordx4 v[48:51], v6, s[30:31]
	global_load_dwordx4 v[52:55], v6, s[30:31] offset:1024
	global_load_dwordx4 v[56:59], v6, s[30:31] offset:2048
	global_load_dwordx4 v[60:63], v6, s[30:31] offset:3072
	s_lshl_b32 s37, s27, 11
	s_add_u32 s38, s16, s37
	s_addc_u32 s39, s17, 0
	s_lshl_b32 s37, s27, 6
	s_add_u32 s42, s40, s37
	s_addc_u32 s43, s41, 0
	s_waitcnt vmcnt(12)
	v_cvt_pk_bf16_f32 v12, v32, v33
	v_cvt_pk_bf16_f32 v13, v34, v35
	global_store_dwordx2 v7, v[12:13], s[38:39]
	v_mul_f32_e32 v3, v33, v33
	v_mul_f32_e32 v8, v35, v35
	v_fmac_f32_e32 v3, v32, v32
	v_fmac_f32_e32 v8, v34, v34
	v_add_f32_e32 v3, v3, v8
	s_waitcnt vmcnt(12)
	v_cvt_pk_bf16_f32 v12, v36, v37
	v_cvt_pk_bf16_f32 v13, v38, v39
	global_store_dwordx2 v7, v[12:13], s[38:39] offset:512
	v_mul_f32_e32 v9, v37, v37
	v_mul_f32_e32 v8, v39, v39
	v_fmac_f32_e32 v9, v36, v36
	v_fmac_f32_e32 v8, v38, v38
	v_add_f32_e32 v9, v9, v8
	v_add_f32_e32 v3, v3, v9
	s_waitcnt vmcnt(12)
	v_cvt_pk_bf16_f32 v12, v40, v41
	v_cvt_pk_bf16_f32 v13, v42, v43
	global_store_dwordx2 v7, v[12:13], s[38:39] offset:1024
	v_mul_f32_e32 v9, v41, v41
	v_mul_f32_e32 v8, v43, v43
	v_fmac_f32_e32 v9, v40, v40
	v_fmac_f32_e32 v8, v42, v42
	v_add_f32_e32 v9, v9, v8
	v_add_f32_e32 v3, v3, v9
	s_waitcnt vmcnt(12)
	v_cvt_pk_bf16_f32 v12, v44, v45
	v_cvt_pk_bf16_f32 v13, v46, v47
	global_store_dwordx2 v7, v[12:13], s[38:39] offset:1536
	v_mul_f32_e32 v9, v45, v45
	v_mul_f32_e32 v8, v47, v47
	v_fmac_f32_e32 v9, v44, v44
	v_fmac_f32_e32 v8, v46, v46
	v_add_f32_e32 v9, v9, v8
	v_add_f32_e32 v3, v3, v9
	s_nop 1
	v_add_f32_dpp v3, v3, v3 quad_perm:[1,0,3,2] row_mask:0xf bank_mask:0xf bound_ctrl:1
	s_nop 1
	v_add_f32_dpp v3, v3, v3 quad_perm:[2,3,0,1] row_mask:0xf bank_mask:0xf bound_ctrl:1
	s_nop 1
	v_add_f32_dpp v3, v3, v3 row_half_mirror row_mask:0xf bank_mask:0xf bound_ctrl:1
	s_nop 1
	v_add_f32_dpp v3, v3, v3 row_mirror row_mask:0xf bank_mask:0xf bound_ctrl:1
	v_mov_b32_e32 v8, v3
	s_nop 1
	v_permlane16_swap_b32_e32 v3, v8
	v_add_f32_e32 v3, v3, v8
	v_mov_b32_e32 v8, v3
	s_nop 1
	v_permlane32_swap_b32_e32 v3, v8
	v_add_f32_e32 v3, v3, v8
	v_cndmask_b32_e64 v3, 0, v3, s[6:7]
	s_and_saveexec_b64 s[8:9], s[28:29]
	global_store_dword v2, v3, s[42:43]
	s_or_b64 exec, exec, s[8:9]
	s_cmp_gt_i32 s35, 0x7fff
	s_cbranch_scc1 .Lp0a_done
	s_mov_b32 s27, s35
	s_branch .Lp0a_loop
.Lp0a_done:
	s_waitcnt vmcnt(0)
.LBB0_34:
	s_or_b64 exec, exec, s[12:13]
	v_lshlrev_b32_e32 v0, 2, v192
	v_and_b32_e32 v10, 60, v0
	v_lshlrev_b32_e32 v0, 3, v192
	v_lshrrev_b32_e32 v11, 3, v192
	v_and_b32_e32 v0, 56, v0
	v_lshrrev_b32_e32 v8, 4, v192
	v_mul_u32_u24_e32 v2, 0x90, v11
	v_lshlrev_b32_e32 v3, 1, v0
	v_mov_b32_e32 v13, 0
	v_mul_u32_u24_e32 v1, 0x90, v10
	v_add3_u32 v18, 0, v2, v3
	v_lshlrev_b32_e32 v2, 1, v8
	s_mov_b32 s3, 0
	v_add3_u32 v19, 0, v1, v2
	v_add_u32_e32 v20, 32, v8
	v_mov_b32_e32 v9, v13
	s_lshl_b32 s30, s2, 6
	v_lshlrev_b32_e32 v12, 1, v0
	v_lshlrev_b32_e32 v14, 2, v10
	s_branch .LBB0_36

.LBB0_557:
	s_bitcmp1_b32 s63, 0
	s_cbranch_scc1 .Lscan_wall
	s_waitcnt vmcnt(8)
	s_branch .Lscan_wdone
.Lscan_wall:
	s_waitcnt vmcnt(0)
.Lscan_wdone:
	s_mov_b32 s84, s69
	v_mov_b32_e32 v113, v192
	s_and_b64 vcc, exec, s[10:11]
	s_mov_b64 s[12:13], -1
	s_cbranch_vccnz .LBB0_561
	v_lshlrev_b32_e32 v16, 4, v113
	v_and_b32_e32 v17, 0xf0, v16
	v_add_u32_e32 v18, 0, v17
	v_lshrrev_b32_e32 v17, 4, v113
	v_mad_u64_u32 v[22:23], s[12:13], v17, s53, v[18:19]
	v_add_u32_e32 v17, 0x200, v113
	v_lshrrev_b32_e32 v17, 4, v17
	v_mad_u64_u32 v[18:19], s[12:13], v17, s53, v[18:19]
	v_lshrrev_b32_e32 v17, 3, v113
	ds_write_b128 v22, v[24:27]
	ds_write_b128 v22, v[32:35] offset:17408
	ds_write_b128 v22, v[40:43] offset:34816
	ds_write_b128 v18, v[28:31]
	ds_write_b128 v18, v[36:39] offset:17408
	ds_write_b128 v18, v[44:47] offset:34816
	v_mul_lo_u32 v17, v17, s54
	v_and_b32_e32 v18, 0x70, v16
	v_add3_u32 v17, 0, v17, v18
	v_cmp_gt_i32_e32 vcc, 32, v113
	ds_write_b128 v17, v[92:95] offset:52224
	s_and_saveexec_b64 s[12:13], vcc
	v_add_u32_e32 v16, 0, v16
	v_add_u32_e32 v16, 0x19800, v16
	ds_write_b128 v16, v[88:91]
	s_or_b64 exec, exec, s[12:13]
	s_mov_b64 s[12:13], 0

.LBB0_597:
	v_cvt_pk_bf16_f32 v56, v56, s0
	v_lshrrev_b32_e32 v57, 2, v107
	ds_write_b16 v20, v56 offset:61872
	v_lshlrev_b32_e32 v20, 3, v113
	v_lshl_or_b32 v60, v60, 3, v57
	v_add_u32_e32 v56, s73, v133
	s_waitcnt lgkmcnt(4)
	v_and_b32_e32 v61, 24, v20
	v_mul_u32_u24_e32 v57, 0x110, v60
	v_add3_u32 v114, s81, v61, v57
	ds_read_b128 v[56:59], v56
	v_mad_u32_u24 v130, v60, s54, v61
	v_add_u32_e32 v115, s66, v130
	ds_read_b64_tr_b16 v[146:147], v114 offset:0
	ds_read_b64_tr_b16 v[148:149], v114 offset:1088
	ds_read_b64_tr_b16 v[142:143], v114 offset:8704
	ds_read_b64_tr_b16 v[144:145], v114 offset:9792
	ds_read_b64_tr_b16 v[138:139], v115 offset:0
	ds_read_b64_tr_b16 v[140:141], v115 offset:576
	ds_read_b64_tr_b16 v[134:135], v115 offset:4608
	ds_read_b64_tr_b16 v[136:137], v115 offset:5184
	ds_read_b64_tr_b16 v[100:101], v115 offset:32
	ds_read_b64_tr_b16 v[102:103], v115 offset:608
	ds_read_b64_tr_b16 v[76:77], v115 offset:4640
	ds_read_b64_tr_b16 v[78:79], v115 offset:5216
	ds_read_b64_tr_b16 v[72:73], v115 offset:64
	ds_read_b64_tr_b16 v[74:75], v115 offset:640
	ds_read_b64_tr_b16 v[68:69], v115 offset:4672
	ds_read_b64_tr_b16 v[70:71], v115 offset:5248
	ds_read_b64_tr_b16 v[64:65], v115 offset:96
	ds_read_b64_tr_b16 v[66:67], v115 offset:672
	ds_read_b64_tr_b16 v[60:61], v115 offset:4704
	ds_read_b64_tr_b16 v[62:63], v115 offset:5280
	s_waitcnt lgkmcnt(0)
	s_cmp_eq_u32 s83, 63
	s_waitcnt lgkmcnt(0)
	v_pk_mul_f32 v[2:3], v[2:3], v[58:59]
	v_pk_mul_f32 v[0:1], v[0:1], v[56:57]
	v_pk_mul_f32 v[6:7], v[6:7], v[58:59]
	v_pk_mul_f32 v[4:5], v[4:5], v[56:57]
	v_pk_mul_f32 v[10:11], v[10:11], v[58:59]
	v_pk_mul_f32 v[8:9], v[8:9], v[56:57]
	v_pk_mul_f32 v[14:15], v[14:15], v[58:59]
	v_pk_mul_f32 v[12:13], v[12:13], v[56:57]
	v_mfma_f32_16x16x32_bf16 v[0:3], v[146:149], v[138:141], v[0:3]
	v_mfma_f32_16x16x32_bf16 v[4:7], v[146:149], v[100:103], v[4:7]
	v_mfma_f32_16x16x32_bf16 v[8:11], v[146:149], v[72:75], v[8:11]
	v_mfma_f32_16x16x32_bf16 v[12:15], v[146:149], v[64:67], v[12:15]
	v_mfma_f32_16x16x32_bf16 v[0:3], v[142:145], v[134:137], v[0:3]
	v_mfma_f32_16x16x32_bf16 v[4:7], v[142:145], v[76:79], v[4:7]
	v_mfma_f32_16x16x32_bf16 v[8:11], v[142:145], v[68:71], v[8:11]
	v_mfma_f32_16x16x32_bf16 v[12:15], v[142:145], v[60:63], v[12:15]
	s_cbranch_scc1 .LBB0_605
	s_add_i32 s50, s69, 64
	v_and_b32_e32 v24, 0x78, v20
	v_ashrrev_i32_e32 v25, 4, v113
	v_add_u32_e32 v26, 0x200, v113
	v_ashrrev_i32_e32 v27, 3, v113
	v_and_b32_e32 v28, 56, v20
	s_mov_b64 s[12:13], -1
	s_and_b64 vcc, exec, s[10:11]
	v_lshlrev_b32_e32 v20, 1, v24
	v_add_u32_e32 v24, s50, v25
	v_ashrrev_i32_e32 v32, 4, v26
	v_add_u32_e32 v26, s50, v27
	v_lshlrev_b32_e32 v114, 1, v28
	s_cbranch_vccnz .LBB0_602
	v_mov_b32_e32 v56, v24
	v_mov_b32_e32 v58, v26
	v_add_u32_e32 v62, s50, v32
	v_lshl_add_u64 v[60:61], s[36:37], 0, v[20:21]
	v_ashrrev_i32_e32 v57, 31, v56
	v_mad_i64_i32 v[64:65], s[12:13], v56, s3, v[60:61]
	v_lshl_add_u64 v[66:67], s[38:39], 0, v[20:21]
	global_load_dwordx4 v[24:27], v[64:65], off
	global_load_dwordx4 v[32:35], v[64:65], off offset:1024
	v_lshlrev_b64 v[64:65], 10, v[56:57]
	v_lshl_add_u64 v[64:65], v[66:67], 0, v[64:65]
	global_load_dwordx4 v[40:43], v[64:65], off
	v_ashrrev_i32_e32 v63, 31, v62
	v_mad_i64_i32 v[60:61], s[12:13], v62, s3, v[60:61]
	global_load_dwordx4 v[28:31], v[60:61], off
	global_load_dwordx4 v[36:39], v[60:61], off offset:1024
	v_lshlrev_b64 v[60:61], 10, v[62:63]
	v_lshl_add_u64 v[60:61], v[66:67], 0, v[60:61]
	global_load_dwordx4 v[44:47], v[60:61], off
	v_mov_b64_e32 v[60:61], s[40:41]
	v_mad_i64_i32 v[60:61], s[12:13], v58, s3, v[60:61]
	v_mov_b32_e32 v115, v21
	v_lshl_add_u64 v[60:61], v[60:61], 0, v[114:115]
	global_load_dwordx4 v[92:95], v[60:61], off
	v_cmp_gt_i32_e32 vcc, 32, v113
	s_and_saveexec_b64 s[12:13], vcc
	s_cbranch_execz .LBB0_601
	s_add_i32 s86, s82, s83
	s_ashr_i32 s87, s86, 31
	s_lshl_b64 s[86:87], s[86:87], 11
	s_add_u32 s86, s74, s86
	v_lshlrev_b32_e32 v60, 2, v113
	s_addc_u32 s87, s75, s87
	v_ashrrev_i32_e32 v61, 31, v60
	v_lshl_add_u64 v[60:61], v[60:61], 2, s[86:87]
	global_load_dwordx4 v[88:91], v[60:61], off

.LBB0_604:
.LBB0_605:
	v_mul_lo_u32 v20, v132, s54
	v_add3_u32 v20, 0, v20, v133
	s_barrier
	ds_read_b128 v[60:63], v20 offset:61440
	ds_read_b128 v[56:59], v20 offset:61504
	v_add_u32_e32 v20, s79, v130
	v_add_u32_e32 v111, s66, v20
	v_add_u32_e32 v20, s67, v20
	ds_read_b64_tr_b16 v[132:133], v111 offset:0
	ds_read_b64_tr_b16 v[134:135], v111 offset:576
	ds_read_b64_tr_b16 v[100:101], v111 offset:4608
	ds_read_b64_tr_b16 v[102:103], v111 offset:5184
	ds_read_b64_tr_b16 v[76:77], v20 offset:0
	ds_read_b64_tr_b16 v[78:79], v20 offset:576
	ds_read_b64_tr_b16 v[72:73], v20 offset:4608
	ds_read_b64_tr_b16 v[74:75], v20 offset:5184
	ds_read_b64_tr_b16 v[68:69], v20 offset:9216
	ds_read_b64_tr_b16 v[70:71], v20 offset:9792
	ds_read_b64_tr_b16 v[64:65], v20 offset:13824
	ds_read_b64_tr_b16 v[66:67], v20 offset:14400
	s_waitcnt lgkmcnt(0)
	s_and_b64 vcc, exec, s[10:11]
	v_mfma_f32_16x16x32_bf16 v[76:79], v[16:19], v[76:79], 0
	v_mfma_f32_16x16x32_bf16 v[72:75], v[80:83], v[72:75], v[76:79]
	v_mfma_f32_16x16x32_bf16 v[68:71], v[84:87], v[68:71], v[72:75]
	v_mfma_f32_16x16x32_bf16 v[64:67], v[96:99], v[64:67], v[68:71]
	s_waitcnt lgkmcnt(1)
	v_mfma_f32_16x16x32_bf16 v[68:71], v[60:63], v[132:135], 0
	s_waitcnt lgkmcnt(0)
	v_mfma_f32_16x16x32_bf16 v[68:71], v[56:59], v[100:103], v[68:71]
	s_cbranch_vccnz .LBB0_614
	s_mov_b64 s[50:51], 0
	s_and_b64 vcc, exec, s[24:25]
	s_mov_b64 s[12:13], 0
	s_cbranch_vccz .LBB0_608
	s_nop 2
	v_add_f32_e32 v74, v64, v68
	s_mov_b64 s[12:13], -1
